# pooling (prompt rows): software-pipelined two-bank path for waves with full windows, constant lane masks, 32-bit saddr addressing
# baseline (speedup 1.0000x reference)
.LBB0_221:
	v_mov_b32_e32 v1, v176
	v_readlane_b32 s0, v253, 5
	s_nop 1
	v_add_u32_e32 v0, s0, v1
	s_mov_b32 s0, 0x80000
	v_cmp_gt_i32_e32 vcc, s0, v0
	s_and_saveexec_b64 s[0:1], vcc
	s_cbranch_execz .LBB0_254
	v_lshrrev_b32_e32 v40, 5, v0
	v_and_b32_e32 v41, 0x7ff, v40
	v_cmp_gt_u32_e32 vcc, 15, v41
	s_cbranch_vccnz .Lpool_slow
	v_and_b32_e32 v41, 31, v0
	v_lshrrev_b32_e32 v42, 3, v41
	v_sub_u32_e32 v42, 126, v42
	v_lshlrev_b32_e32 v42, 23, v42
	v_lshlrev_b32_e32 v41, 4, v41
	v_mul_lo_u32 v43, v40, s30
	v_add_u32_e32 v43, v43, v41
	v_add_u32_e32 v43, 0x800, v43
	v_lshl_add_u32 v44, v40, 11, v41
	s_lshl_b32 s11, s30, 12
	s_mov_b32 s12, 0xffffff00
	s_mov_b32 s13, 0xffffff00
	s_mov_b32 s14, 0xffff0000
	s_mov_b32 s15, 0xffff0000
	s_mov_b32 s16, 0xff000000
	s_mov_b32 s17, 0xff000000
	v_mov_b64_e32 v[104:105], 0
	v_mov_b64_e32 v[106:107], 0
	v_mov_b64_e32 v[108:109], 0
	v_mov_b64_e32 v[110:111], 0
	v_mov_b64_e32 v[112:113], 0
	v_mov_b64_e32 v[114:115], 0
	v_mov_b64_e32 v[116:117], 0
	v_mov_b64_e32 v[118:119], 0
	v_mov_b64_e32 v[120:121], 0
	v_mov_b64_e32 v[122:123], 0
	v_mov_b64_e32 v[124:125], 0
	v_mov_b64_e32 v[126:127], 0
	v_mov_b64_e32 v[128:129], 0
	v_mov_b64_e32 v[130:131], 0
	v_mov_b64_e32 v[132:133], 0
	v_mov_b64_e32 v[134:135], 0
	v_mov_b64_e32 v[136:137], 0
	v_mov_b64_e32 v[138:139], 0
	v_mov_b64_e32 v[140:141], 0
	v_mov_b64_e32 v[142:143], 0
	v_mov_b64_e32 v[144:145], 0
	v_mov_b64_e32 v[146:147], 0
	v_mov_b64_e32 v[158:159], 0
	v_mov_b64_e32 v[160:161], 0
	v_mov_b64_e32 v[162:163], 0
	v_mov_b64_e32 v[164:165], 0
	v_mov_b64_e32 v[166:167], 0
	v_mov_b64_e32 v[168:169], 0
	v_mov_b64_e32 v[198:199], 0
	v_mov_b64_e32 v[200:201], 0
	v_mov_b64_e32 v[202:203], 0
	v_mov_b64_e32 v[204:205], 0
	v_mov_b64_e32 v[206:207], 0
	v_mov_b64_e32 v[208:209], 0
	v_mov_b64_e32 v[210:211], 0
	v_mov_b64_e32 v[212:213], 0
	v_mov_b64_e32 v[214:215], 0
	v_mov_b64_e32 v[216:217], 0
	v_mov_b64_e32 v[218:219], 0
	v_mov_b64_e32 v[220:221], 0
	v_mov_b64_e32 v[222:223], 0
	v_mov_b64_e32 v[224:225], 0
	v_mov_b64_e32 v[226:227], 0
	v_mov_b64_e32 v[228:229], 0
	v_mov_b64_e32 v[230:231], 0
	v_mov_b64_e32 v[232:233], 0
	v_mov_b64_e32 v[234:235], 0
	v_mov_b64_e32 v[236:237], 0
	v_mov_b64_e32 v[238:239], 0
	v_mov_b64_e32 v[240:241], 0
	v_mov_b64_e32 v[242:243], 0
	v_mov_b64_e32 v[244:245], 0
	v_mov_b64_e32 v[246:247], 0
	v_mov_b64_e32 v[248:249], 0
	v_mov_b64_e32 v[170:171], 0
	v_mov_b64_e32 v[172:173], 0
	global_load_dwordx4 v[96:99], v43, s[80:81]
	v_subrev_u32_e32 v45, s30, v43
	global_load_dwordx4 v[100:103], v45, s[80:81]
	s_mov_b64 exec, s[12:13]
	v_subrev_u32_e32 v45, s30, v45
	global_load_dwordx4 v[104:107], v45, s[80:81]
	v_subrev_u32_e32 v45, s30, v45
	global_load_dwordx4 v[108:111], v45, s[80:81]
	s_mov_b64 exec, s[14:15]
	v_subrev_u32_e32 v45, s30, v45
	global_load_dwordx4 v[112:115], v45, s[80:81]
	v_subrev_u32_e32 v45, s30, v45
	global_load_dwordx4 v[116:119], v45, s[80:81]
	v_subrev_u32_e32 v45, s30, v45
	global_load_dwordx4 v[120:123], v45, s[80:81]
	v_subrev_u32_e32 v45, s30, v45
	global_load_dwordx4 v[124:127], v45, s[80:81]
	s_mov_b64 exec, s[16:17]
	v_subrev_u32_e32 v45, s30, v45
	global_load_dwordx4 v[128:131], v45, s[80:81]
	v_subrev_u32_e32 v45, s30, v45
	global_load_dwordx4 v[132:135], v45, s[80:81]
	v_subrev_u32_e32 v45, s30, v45
	global_load_dwordx4 v[136:139], v45, s[80:81]
	v_subrev_u32_e32 v45, s30, v45
	global_load_dwordx4 v[140:143], v45, s[80:81]
	v_subrev_u32_e32 v45, s30, v45
	global_load_dwordx4 v[144:147], v45, s[80:81]
	v_subrev_u32_e32 v45, s30, v45
	global_load_dwordx4 v[158:161], v45, s[80:81]
	v_subrev_u32_e32 v45, s30, v45
	global_load_dwordx4 v[162:165], v45, s[80:81]
	v_subrev_u32_e32 v45, s30, v45
	global_load_dwordx4 v[166:169], v45, s[80:81]
	s_mov_b64 exec, -1
	v_add_u32_e32 v43, s11, v43
	global_load_dwordx4 v[190:193], v43, s[80:81]
	v_subrev_u32_e32 v45, s30, v43
	global_load_dwordx4 v[194:197], v45, s[80:81]
	s_mov_b64 exec, s[12:13]
	v_subrev_u32_e32 v45, s30, v45
	global_load_dwordx4 v[198:201], v45, s[80:81]
	v_subrev_u32_e32 v45, s30, v45
	global_load_dwordx4 v[202:205], v45, s[80:81]
	s_mov_b64 exec, s[14:15]
	v_subrev_u32_e32 v45, s30, v45
	global_load_dwordx4 v[206:209], v45, s[80:81]
	v_subrev_u32_e32 v45, s30, v45
	global_load_dwordx4 v[210:213], v45, s[80:81]
	v_subrev_u32_e32 v45, s30, v45
	global_load_dwordx4 v[214:217], v45, s[80:81]
	v_subrev_u32_e32 v45, s30, v45
	global_load_dwordx4 v[218:221], v45, s[80:81]
	s_mov_b64 exec, s[16:17]
	v_subrev_u32_e32 v45, s30, v45
	global_load_dwordx4 v[222:225], v45, s[80:81]
	v_subrev_u32_e32 v45, s30, v45
	global_load_dwordx4 v[226:229], v45, s[80:81]
	v_subrev_u32_e32 v45, s30, v45
	global_load_dwordx4 v[230:233], v45, s[80:81]
	v_subrev_u32_e32 v45, s30, v45
	global_load_dwordx4 v[234:237], v45, s[80:81]
	v_subrev_u32_e32 v45, s30, v45
	global_load_dwordx4 v[238:241], v45, s[80:81]
	v_subrev_u32_e32 v45, s30, v45
	global_load_dwordx4 v[242:245], v45, s[80:81]
	v_subrev_u32_e32 v45, s30, v45
	global_load_dwordx4 v[246:249], v45, s[80:81]
	v_subrev_u32_e32 v45, s30, v45
	global_load_dwordx4 v[170:173], v45, s[80:81]
	s_mov_b64 exec, -1
	v_add_u32_e32 v43, s11, v43
	s_waitcnt vmcnt(16)
	v_lshlrev_b32_e32 v54, 16, v100
	v_and_b32_e32 v58, 0xffff0000, v100
	v_lshlrev_b32_e32 v55, 16, v101
	v_and_b32_e32 v59, 0xffff0000, v101
	v_lshlrev_b32_e32 v56, 16, v102
	v_and_b32_e32 v60, 0xffff0000, v102
	v_lshlrev_b32_e32 v57, 16, v103
	v_and_b32_e32 v61, 0xffff0000, v103
	v_add_f32_e32 v46, 0, v54
	v_add_f32_e32 v50, 0, v58
	v_add_f32_e32 v47, 0, v55
	v_add_f32_e32 v51, 0, v59
	v_add_f32_e32 v48, 0, v56
	v_add_f32_e32 v52, 0, v60
	v_add_f32_e32 v49, 0, v57
	v_add_f32_e32 v53, 0, v61
	v_lshlrev_b32_e32 v54, 16, v104
	v_and_b32_e32 v58, 0xffff0000, v104
	v_lshlrev_b32_e32 v55, 16, v105
	v_and_b32_e32 v59, 0xffff0000, v105
	v_lshlrev_b32_e32 v56, 16, v106
	v_and_b32_e32 v60, 0xffff0000, v106
	v_lshlrev_b32_e32 v57, 16, v107
	v_and_b32_e32 v61, 0xffff0000, v107
	v_add_f32_e32 v46, v46, v54
	v_add_f32_e32 v50, v50, v58
	v_add_f32_e32 v47, v47, v55
	v_add_f32_e32 v51, v51, v59
	v_add_f32_e32 v48, v48, v56
	v_add_f32_e32 v52, v52, v60
	v_add_f32_e32 v49, v49, v57
	v_add_f32_e32 v53, v53, v61
	v_lshlrev_b32_e32 v54, 16, v108
	v_and_b32_e32 v58, 0xffff0000, v108
	v_lshlrev_b32_e32 v55, 16, v109
	v_and_b32_e32 v59, 0xffff0000, v109
	v_lshlrev_b32_e32 v56, 16, v110
	v_and_b32_e32 v60, 0xffff0000, v110
	v_lshlrev_b32_e32 v57, 16, v111
	v_and_b32_e32 v61, 0xffff0000, v111
	v_add_f32_e32 v46, v46, v54
	v_add_f32_e32 v50, v50, v58
	v_add_f32_e32 v47, v47, v55
	v_add_f32_e32 v51, v51, v59
	v_add_f32_e32 v48, v48, v56
	v_add_f32_e32 v52, v52, v60
	v_add_f32_e32 v49, v49, v57
	v_add_f32_e32 v53, v53, v61
	v_lshlrev_b32_e32 v54, 16, v112
	v_and_b32_e32 v58, 0xffff0000, v112
	v_lshlrev_b32_e32 v55, 16, v113
	v_and_b32_e32 v59, 0xffff0000, v113
	v_lshlrev_b32_e32 v56, 16, v114
	v_and_b32_e32 v60, 0xffff0000, v114
	v_lshlrev_b32_e32 v57, 16, v115
	v_and_b32_e32 v61, 0xffff0000, v115
	v_add_f32_e32 v46, v46, v54
	v_add_f32_e32 v50, v50, v58
	v_add_f32_e32 v47, v47, v55
	v_add_f32_e32 v51, v51, v59
	v_add_f32_e32 v48, v48, v56
	v_add_f32_e32 v52, v52, v60
	v_add_f32_e32 v49, v49, v57
	v_add_f32_e32 v53, v53, v61
	v_lshlrev_b32_e32 v54, 16, v116
	v_and_b32_e32 v58, 0xffff0000, v116
	v_lshlrev_b32_e32 v55, 16, v117
	v_and_b32_e32 v59, 0xffff0000, v117
	v_lshlrev_b32_e32 v56, 16, v118
	v_and_b32_e32 v60, 0xffff0000, v118
	v_lshlrev_b32_e32 v57, 16, v119
	v_and_b32_e32 v61, 0xffff0000, v119
	v_add_f32_e32 v46, v46, v54
	v_add_f32_e32 v50, v50, v58
	v_add_f32_e32 v47, v47, v55
	v_add_f32_e32 v51, v51, v59
	v_add_f32_e32 v48, v48, v56
	v_add_f32_e32 v52, v52, v60
	v_add_f32_e32 v49, v49, v57
	v_add_f32_e32 v53, v53, v61
	v_lshlrev_b32_e32 v54, 16, v120
	v_and_b32_e32 v58, 0xffff0000, v120
	v_lshlrev_b32_e32 v55, 16, v121
	v_and_b32_e32 v59, 0xffff0000, v121
	v_lshlrev_b32_e32 v56, 16, v122
	v_and_b32_e32 v60, 0xffff0000, v122
	v_lshlrev_b32_e32 v57, 16, v123
	v_and_b32_e32 v61, 0xffff0000, v123
	v_add_f32_e32 v46, v46, v54
	v_add_f32_e32 v50, v50, v58
	v_add_f32_e32 v47, v47, v55
	v_add_f32_e32 v51, v51, v59
	v_add_f32_e32 v48, v48, v56
	v_add_f32_e32 v52, v52, v60
	v_add_f32_e32 v49, v49, v57
	v_add_f32_e32 v53, v53, v61
	v_lshlrev_b32_e32 v54, 16, v124
	v_and_b32_e32 v58, 0xffff0000, v124
	v_lshlrev_b32_e32 v55, 16, v125
	v_and_b32_e32 v59, 0xffff0000, v125
	v_lshlrev_b32_e32 v56, 16, v126
	v_and_b32_e32 v60, 0xffff0000, v126
	v_lshlrev_b32_e32 v57, 16, v127
	v_and_b32_e32 v61, 0xffff0000, v127
	v_add_f32_e32 v46, v46, v54
	v_add_f32_e32 v50, v50, v58
	v_add_f32_e32 v47, v47, v55
	v_add_f32_e32 v51, v51, v59
	v_add_f32_e32 v48, v48, v56
	v_add_f32_e32 v52, v52, v60
	v_add_f32_e32 v49, v49, v57
	v_add_f32_e32 v53, v53, v61
	v_lshlrev_b32_e32 v54, 16, v128
	v_and_b32_e32 v58, 0xffff0000, v128
	v_lshlrev_b32_e32 v55, 16, v129
	v_and_b32_e32 v59, 0xffff0000, v129
	v_lshlrev_b32_e32 v56, 16, v130
	v_and_b32_e32 v60, 0xffff0000, v130
	v_lshlrev_b32_e32 v57, 16, v131
	v_and_b32_e32 v61, 0xffff0000, v131
	v_add_f32_e32 v46, v46, v54
	v_add_f32_e32 v50, v50, v58
	v_add_f32_e32 v47, v47, v55
	v_add_f32_e32 v51, v51, v59
	v_add_f32_e32 v48, v48, v56
	v_add_f32_e32 v52, v52, v60
	v_add_f32_e32 v49, v49, v57
	v_add_f32_e32 v53, v53, v61
	v_lshlrev_b32_e32 v54, 16, v132
	v_and_b32_e32 v58, 0xffff0000, v132
	v_lshlrev_b32_e32 v55, 16, v133
	v_and_b32_e32 v59, 0xffff0000, v133
	v_lshlrev_b32_e32 v56, 16, v134
	v_and_b32_e32 v60, 0xffff0000, v134
	v_lshlrev_b32_e32 v57, 16, v135
	v_and_b32_e32 v61, 0xffff0000, v135
	v_add_f32_e32 v46, v46, v54
	v_add_f32_e32 v50, v50, v58
	v_add_f32_e32 v47, v47, v55
	v_add_f32_e32 v51, v51, v59
	v_add_f32_e32 v48, v48, v56
	v_add_f32_e32 v52, v52, v60
	v_add_f32_e32 v49, v49, v57
	v_add_f32_e32 v53, v53, v61
	v_lshlrev_b32_e32 v54, 16, v136
	v_and_b32_e32 v58, 0xffff0000, v136
	v_lshlrev_b32_e32 v55, 16, v137
	v_and_b32_e32 v59, 0xffff0000, v137
	v_lshlrev_b32_e32 v56, 16, v138
	v_and_b32_e32 v60, 0xffff0000, v138
	v_lshlrev_b32_e32 v57, 16, v139
	v_and_b32_e32 v61, 0xffff0000, v139
	v_add_f32_e32 v46, v46, v54
	v_add_f32_e32 v50, v50, v58
	v_add_f32_e32 v47, v47, v55
	v_add_f32_e32 v51, v51, v59
	v_add_f32_e32 v48, v48, v56
	v_add_f32_e32 v52, v52, v60
	v_add_f32_e32 v49, v49, v57
	v_add_f32_e32 v53, v53, v61
	v_lshlrev_b32_e32 v54, 16, v140
	v_and_b32_e32 v58, 0xffff0000, v140
	v_lshlrev_b32_e32 v55, 16, v141
	v_and_b32_e32 v59, 0xffff0000, v141
	v_lshlrev_b32_e32 v56, 16, v142
	v_and_b32_e32 v60, 0xffff0000, v142
	v_lshlrev_b32_e32 v57, 16, v143
	v_and_b32_e32 v61, 0xffff0000, v143
	v_add_f32_e32 v46, v46, v54
	v_add_f32_e32 v50, v50, v58
	v_add_f32_e32 v47, v47, v55
	v_add_f32_e32 v51, v51, v59
	v_add_f32_e32 v48, v48, v56
	v_add_f32_e32 v52, v52, v60
	v_add_f32_e32 v49, v49, v57
	v_add_f32_e32 v53, v53, v61
	v_lshlrev_b32_e32 v54, 16, v144
	v_and_b32_e32 v58, 0xffff0000, v144
	v_lshlrev_b32_e32 v55, 16, v145
	v_and_b32_e32 v59, 0xffff0000, v145
	v_lshlrev_b32_e32 v56, 16, v146
	v_and_b32_e32 v60, 0xffff0000, v146
	v_lshlrev_b32_e32 v57, 16, v147
	v_and_b32_e32 v61, 0xffff0000, v147
	v_add_f32_e32 v46, v46, v54
	v_add_f32_e32 v50, v50, v58
	v_add_f32_e32 v47, v47, v55
	v_add_f32_e32 v51, v51, v59
	v_add_f32_e32 v48, v48, v56
	v_add_f32_e32 v52, v52, v60
	v_add_f32_e32 v49, v49, v57
	v_add_f32_e32 v53, v53, v61
	v_lshlrev_b32_e32 v54, 16, v158
	v_and_b32_e32 v58, 0xffff0000, v158
	v_lshlrev_b32_e32 v55, 16, v159
	v_and_b32_e32 v59, 0xffff0000, v159
	v_lshlrev_b32_e32 v56, 16, v160
	v_and_b32_e32 v60, 0xffff0000, v160
	v_lshlrev_b32_e32 v57, 16, v161
	v_and_b32_e32 v61, 0xffff0000, v161
	v_add_f32_e32 v46, v46, v54
	v_add_f32_e32 v50, v50, v58
	v_add_f32_e32 v47, v47, v55
	v_add_f32_e32 v51, v51, v59
	v_add_f32_e32 v48, v48, v56
	v_add_f32_e32 v52, v52, v60
	v_add_f32_e32 v49, v49, v57
	v_add_f32_e32 v53, v53, v61
	v_lshlrev_b32_e32 v54, 16, v162
	v_and_b32_e32 v58, 0xffff0000, v162
	v_lshlrev_b32_e32 v55, 16, v163
	v_and_b32_e32 v59, 0xffff0000, v163
	v_lshlrev_b32_e32 v56, 16, v164
	v_and_b32_e32 v60, 0xffff0000, v164
	v_lshlrev_b32_e32 v57, 16, v165
	v_and_b32_e32 v61, 0xffff0000, v165
	v_add_f32_e32 v46, v46, v54
	v_add_f32_e32 v50, v50, v58
	v_add_f32_e32 v47, v47, v55
	v_add_f32_e32 v51, v51, v59
	v_add_f32_e32 v48, v48, v56
	v_add_f32_e32 v52, v52, v60
	v_add_f32_e32 v49, v49, v57
	v_add_f32_e32 v53, v53, v61
	v_lshlrev_b32_e32 v54, 16, v166
	v_and_b32_e32 v58, 0xffff0000, v166
	v_lshlrev_b32_e32 v55, 16, v167
	v_and_b32_e32 v59, 0xffff0000, v167
	v_lshlrev_b32_e32 v56, 16, v168
	v_and_b32_e32 v60, 0xffff0000, v168
	v_lshlrev_b32_e32 v57, 16, v169
	v_and_b32_e32 v61, 0xffff0000, v169
	v_add_f32_e32 v46, v46, v54
	v_add_f32_e32 v50, v50, v58
	v_add_f32_e32 v47, v47, v55
	v_add_f32_e32 v51, v51, v59
	v_add_f32_e32 v48, v48, v56
	v_add_f32_e32 v52, v52, v60
	v_add_f32_e32 v49, v49, v57
	v_add_f32_e32 v53, v53, v61
	v_lshlrev_b32_e32 v54, 16, v96
	v_and_b32_e32 v58, 0xffff0000, v96
	v_lshlrev_b32_e32 v55, 16, v97
	v_and_b32_e32 v59, 0xffff0000, v97
	v_lshlrev_b32_e32 v56, 16, v98
	v_and_b32_e32 v60, 0xffff0000, v98
	v_lshlrev_b32_e32 v57, 16, v99
	v_and_b32_e32 v61, 0xffff0000, v99
	v_add_f32_e32 v46, v46, v54
	v_add_f32_e32 v50, v50, v58
	v_add_f32_e32 v47, v47, v55
	v_add_f32_e32 v51, v51, v59
	v_add_f32_e32 v48, v48, v56
	v_add_f32_e32 v52, v52, v60
	v_add_f32_e32 v49, v49, v57
	v_add_f32_e32 v53, v53, v61
	v_fma_f32 v46, v42, v46, -v54
	v_fma_f32 v50, v42, v50, -v58
	v_fma_f32 v47, v42, v47, -v55
	v_fma_f32 v51, v42, v51, -v59
	v_fma_f32 v48, v42, v48, -v56
	v_fma_f32 v52, v42, v52, -v60
	v_fma_f32 v49, v42, v49, -v57
	v_fma_f32 v53, v42, v53, -v61
	v_cvt_pk_bf16_f32 v46, v46, v50
	v_cvt_pk_bf16_f32 v47, v47, v51
	v_cvt_pk_bf16_f32 v48, v48, v52
	v_cvt_pk_bf16_f32 v49, v49, v53
	global_store_dwordx4 v44, v[46:49], s[62:63] offset:1024
	v_add_u32_e32 v44, 0x800000, v44
	global_load_dwordx4 v[96:99], v43, s[80:81]
	v_subrev_u32_e32 v45, s30, v43
	global_load_dwordx4 v[100:103], v45, s[80:81]
	s_mov_b64 exec, s[12:13]
	v_subrev_u32_e32 v45, s30, v45
	global_load_dwordx4 v[104:107], v45, s[80:81]
	v_subrev_u32_e32 v45, s30, v45
	global_load_dwordx4 v[108:111], v45, s[80:81]
	s_mov_b64 exec, s[14:15]
	v_subrev_u32_e32 v45, s30, v45
	global_load_dwordx4 v[112:115], v45, s[80:81]
	v_subrev_u32_e32 v45, s30, v45
	global_load_dwordx4 v[116:119], v45, s[80:81]
	v_subrev_u32_e32 v45, s30, v45
	global_load_dwordx4 v[120:123], v45, s[80:81]
	v_subrev_u32_e32 v45, s30, v45
	global_load_dwordx4 v[124:127], v45, s[80:81]
	s_mov_b64 exec, s[16:17]
	v_subrev_u32_e32 v45, s30, v45
	global_load_dwordx4 v[128:131], v45, s[80:81]
	v_subrev_u32_e32 v45, s30, v45
	global_load_dwordx4 v[132:135], v45, s[80:81]
	v_subrev_u32_e32 v45, s30, v45
	global_load_dwordx4 v[136:139], v45, s[80:81]
	v_subrev_u32_e32 v45, s30, v45
	global_load_dwordx4 v[140:143], v45, s[80:81]
	v_subrev_u32_e32 v45, s30, v45
	global_load_dwordx4 v[144:147], v45, s[80:81]
	v_subrev_u32_e32 v45, s30, v45
	global_load_dwordx4 v[158:161], v45, s[80:81]
	v_subrev_u32_e32 v45, s30, v45
	global_load_dwordx4 v[162:165], v45, s[80:81]
	v_subrev_u32_e32 v45, s30, v45
	global_load_dwordx4 v[166:169], v45, s[80:81]
	s_mov_b64 exec, -1
	v_add_u32_e32 v43, s11, v43
	s_waitcnt vmcnt(17)
	v_lshlrev_b32_e32 v54, 16, v194
	v_and_b32_e32 v58, 0xffff0000, v194
	v_lshlrev_b32_e32 v55, 16, v195
	v_and_b32_e32 v59, 0xffff0000, v195
	v_lshlrev_b32_e32 v56, 16, v196
	v_and_b32_e32 v60, 0xffff0000, v196
	v_lshlrev_b32_e32 v57, 16, v197
	v_and_b32_e32 v61, 0xffff0000, v197
	v_add_f32_e32 v46, 0, v54
	v_add_f32_e32 v50, 0, v58
	v_add_f32_e32 v47, 0, v55
	v_add_f32_e32 v51, 0, v59
	v_add_f32_e32 v48, 0, v56
	v_add_f32_e32 v52, 0, v60
	v_add_f32_e32 v49, 0, v57
	v_add_f32_e32 v53, 0, v61
	v_lshlrev_b32_e32 v54, 16, v198
	v_and_b32_e32 v58, 0xffff0000, v198
	v_lshlrev_b32_e32 v55, 16, v199
	v_and_b32_e32 v59, 0xffff0000, v199
	v_lshlrev_b32_e32 v56, 16, v200
	v_and_b32_e32 v60, 0xffff0000, v200
	v_lshlrev_b32_e32 v57, 16, v201
	v_and_b32_e32 v61, 0xffff0000, v201
	v_add_f32_e32 v46, v46, v54
	v_add_f32_e32 v50, v50, v58
	v_add_f32_e32 v47, v47, v55
	v_add_f32_e32 v51, v51, v59
	v_add_f32_e32 v48, v48, v56
	v_add_f32_e32 v52, v52, v60
	v_add_f32_e32 v49, v49, v57
	v_add_f32_e32 v53, v53, v61
	v_lshlrev_b32_e32 v54, 16, v202
	v_and_b32_e32 v58, 0xffff0000, v202
	v_lshlrev_b32_e32 v55, 16, v203
	v_and_b32_e32 v59, 0xffff0000, v203
	v_lshlrev_b32_e32 v56, 16, v204
	v_and_b32_e32 v60, 0xffff0000, v204
	v_lshlrev_b32_e32 v57, 16, v205
	v_and_b32_e32 v61, 0xffff0000, v205
	v_add_f32_e32 v46, v46, v54
	v_add_f32_e32 v50, v50, v58
	v_add_f32_e32 v47, v47, v55
	v_add_f32_e32 v51, v51, v59
	v_add_f32_e32 v48, v48, v56
	v_add_f32_e32 v52, v52, v60
	v_add_f32_e32 v49, v49, v57
	v_add_f32_e32 v53, v53, v61
	v_lshlrev_b32_e32 v54, 16, v206
	v_and_b32_e32 v58, 0xffff0000, v206
	v_lshlrev_b32_e32 v55, 16, v207
	v_and_b32_e32 v59, 0xffff0000, v207
	v_lshlrev_b32_e32 v56, 16, v208
	v_and_b32_e32 v60, 0xffff0000, v208
	v_lshlrev_b32_e32 v57, 16, v209
	v_and_b32_e32 v61, 0xffff0000, v209
	v_add_f32_e32 v46, v46, v54
	v_add_f32_e32 v50, v50, v58
	v_add_f32_e32 v47, v47, v55
	v_add_f32_e32 v51, v51, v59
	v_add_f32_e32 v48, v48, v56
	v_add_f32_e32 v52, v52, v60
	v_add_f32_e32 v49, v49, v57
	v_add_f32_e32 v53, v53, v61
	v_lshlrev_b32_e32 v54, 16, v210
	v_and_b32_e32 v58, 0xffff0000, v210
	v_lshlrev_b32_e32 v55, 16, v211
	v_and_b32_e32 v59, 0xffff0000, v211
	v_lshlrev_b32_e32 v56, 16, v212
	v_and_b32_e32 v60, 0xffff0000, v212
	v_lshlrev_b32_e32 v57, 16, v213
	v_and_b32_e32 v61, 0xffff0000, v213
	v_add_f32_e32 v46, v46, v54
	v_add_f32_e32 v50, v50, v58
	v_add_f32_e32 v47, v47, v55
	v_add_f32_e32 v51, v51, v59
	v_add_f32_e32 v48, v48, v56
	v_add_f32_e32 v52, v52, v60
	v_add_f32_e32 v49, v49, v57
	v_add_f32_e32 v53, v53, v61
	v_lshlrev_b32_e32 v54, 16, v214
	v_and_b32_e32 v58, 0xffff0000, v214
	v_lshlrev_b32_e32 v55, 16, v215
	v_and_b32_e32 v59, 0xffff0000, v215
	v_lshlrev_b32_e32 v56, 16, v216
	v_and_b32_e32 v60, 0xffff0000, v216
	v_lshlrev_b32_e32 v57, 16, v217
	v_and_b32_e32 v61, 0xffff0000, v217
	v_add_f32_e32 v46, v46, v54
	v_add_f32_e32 v50, v50, v58
	v_add_f32_e32 v47, v47, v55
	v_add_f32_e32 v51, v51, v59
	v_add_f32_e32 v48, v48, v56
	v_add_f32_e32 v52, v52, v60
	v_add_f32_e32 v49, v49, v57
	v_add_f32_e32 v53, v53, v61
	v_lshlrev_b32_e32 v54, 16, v218
	v_and_b32_e32 v58, 0xffff0000, v218
	v_lshlrev_b32_e32 v55, 16, v219
	v_and_b32_e32 v59, 0xffff0000, v219
	v_lshlrev_b32_e32 v56, 16, v220
	v_and_b32_e32 v60, 0xffff0000, v220
	v_lshlrev_b32_e32 v57, 16, v221
	v_and_b32_e32 v61, 0xffff0000, v221
	v_add_f32_e32 v46, v46, v54
	v_add_f32_e32 v50, v50, v58
	v_add_f32_e32 v47, v47, v55
	v_add_f32_e32 v51, v51, v59
	v_add_f32_e32 v48, v48, v56
	v_add_f32_e32 v52, v52, v60
	v_add_f32_e32 v49, v49, v57
	v_add_f32_e32 v53, v53, v61
	v_lshlrev_b32_e32 v54, 16, v222
	v_and_b32_e32 v58, 0xffff0000, v222
	v_lshlrev_b32_e32 v55, 16, v223
	v_and_b32_e32 v59, 0xffff0000, v223
	v_lshlrev_b32_e32 v56, 16, v224
	v_and_b32_e32 v60, 0xffff0000, v224
	v_lshlrev_b32_e32 v57, 16, v225
	v_and_b32_e32 v61, 0xffff0000, v225
	v_add_f32_e32 v46, v46, v54
	v_add_f32_e32 v50, v50, v58
	v_add_f32_e32 v47, v47, v55
	v_add_f32_e32 v51, v51, v59
	v_add_f32_e32 v48, v48, v56
	v_add_f32_e32 v52, v52, v60
	v_add_f32_e32 v49, v49, v57
	v_add_f32_e32 v53, v53, v61
	v_lshlrev_b32_e32 v54, 16, v226
	v_and_b32_e32 v58, 0xffff0000, v226
	v_lshlrev_b32_e32 v55, 16, v227
	v_and_b32_e32 v59, 0xffff0000, v227
	v_lshlrev_b32_e32 v56, 16, v228
	v_and_b32_e32 v60, 0xffff0000, v228
	v_lshlrev_b32_e32 v57, 16, v229
	v_and_b32_e32 v61, 0xffff0000, v229
	v_add_f32_e32 v46, v46, v54
	v_add_f32_e32 v50, v50, v58
	v_add_f32_e32 v47, v47, v55
	v_add_f32_e32 v51, v51, v59
	v_add_f32_e32 v48, v48, v56
	v_add_f32_e32 v52, v52, v60
	v_add_f32_e32 v49, v49, v57
	v_add_f32_e32 v53, v53, v61
	v_lshlrev_b32_e32 v54, 16, v230
	v_and_b32_e32 v58, 0xffff0000, v230
	v_lshlrev_b32_e32 v55, 16, v231
	v_and_b32_e32 v59, 0xffff0000, v231
	v_lshlrev_b32_e32 v56, 16, v232
	v_and_b32_e32 v60, 0xffff0000, v232
	v_lshlrev_b32_e32 v57, 16, v233
	v_and_b32_e32 v61, 0xffff0000, v233
	v_add_f32_e32 v46, v46, v54
	v_add_f32_e32 v50, v50, v58
	v_add_f32_e32 v47, v47, v55
	v_add_f32_e32 v51, v51, v59
	v_add_f32_e32 v48, v48, v56
	v_add_f32_e32 v52, v52, v60
	v_add_f32_e32 v49, v49, v57
	v_add_f32_e32 v53, v53, v61
	v_lshlrev_b32_e32 v54, 16, v234
	v_and_b32_e32 v58, 0xffff0000, v234
	v_lshlrev_b32_e32 v55, 16, v235
	v_and_b32_e32 v59, 0xffff0000, v235
	v_lshlrev_b32_e32 v56, 16, v236
	v_and_b32_e32 v60, 0xffff0000, v236
	v_lshlrev_b32_e32 v57, 16, v237
	v_and_b32_e32 v61, 0xffff0000, v237
	v_add_f32_e32 v46, v46, v54
	v_add_f32_e32 v50, v50, v58
	v_add_f32_e32 v47, v47, v55
	v_add_f32_e32 v51, v51, v59
	v_add_f32_e32 v48, v48, v56
	v_add_f32_e32 v52, v52, v60
	v_add_f32_e32 v49, v49, v57
	v_add_f32_e32 v53, v53, v61
	v_lshlrev_b32_e32 v54, 16, v238
	v_and_b32_e32 v58, 0xffff0000, v238
	v_lshlrev_b32_e32 v55, 16, v239
	v_and_b32_e32 v59, 0xffff0000, v239
	v_lshlrev_b32_e32 v56, 16, v240
	v_and_b32_e32 v60, 0xffff0000, v240
	v_lshlrev_b32_e32 v57, 16, v241
	v_and_b32_e32 v61, 0xffff0000, v241
	v_add_f32_e32 v46, v46, v54
	v_add_f32_e32 v50, v50, v58
	v_add_f32_e32 v47, v47, v55
	v_add_f32_e32 v51, v51, v59
	v_add_f32_e32 v48, v48, v56
	v_add_f32_e32 v52, v52, v60
	v_add_f32_e32 v49, v49, v57
	v_add_f32_e32 v53, v53, v61
	v_lshlrev_b32_e32 v54, 16, v242
	v_and_b32_e32 v58, 0xffff0000, v242
	v_lshlrev_b32_e32 v55, 16, v243
	v_and_b32_e32 v59, 0xffff0000, v243
	v_lshlrev_b32_e32 v56, 16, v244
	v_and_b32_e32 v60, 0xffff0000, v244
	v_lshlrev_b32_e32 v57, 16, v245
	v_and_b32_e32 v61, 0xffff0000, v245
	v_add_f32_e32 v46, v46, v54
	v_add_f32_e32 v50, v50, v58
	v_add_f32_e32 v47, v47, v55
	v_add_f32_e32 v51, v51, v59
	v_add_f32_e32 v48, v48, v56
	v_add_f32_e32 v52, v52, v60
	v_add_f32_e32 v49, v49, v57
	v_add_f32_e32 v53, v53, v61
	v_lshlrev_b32_e32 v54, 16, v246
	v_and_b32_e32 v58, 0xffff0000, v246
	v_lshlrev_b32_e32 v55, 16, v247
	v_and_b32_e32 v59, 0xffff0000, v247
	v_lshlrev_b32_e32 v56, 16, v248
	v_and_b32_e32 v60, 0xffff0000, v248
	v_lshlrev_b32_e32 v57, 16, v249
	v_and_b32_e32 v61, 0xffff0000, v249
	v_add_f32_e32 v46, v46, v54
	v_add_f32_e32 v50, v50, v58
	v_add_f32_e32 v47, v47, v55
	v_add_f32_e32 v51, v51, v59
	v_add_f32_e32 v48, v48, v56
	v_add_f32_e32 v52, v52, v60
	v_add_f32_e32 v49, v49, v57
	v_add_f32_e32 v53, v53, v61
	v_lshlrev_b32_e32 v54, 16, v170
	v_and_b32_e32 v58, 0xffff0000, v170
	v_lshlrev_b32_e32 v55, 16, v171
	v_and_b32_e32 v59, 0xffff0000, v171
	v_lshlrev_b32_e32 v56, 16, v172
	v_and_b32_e32 v60, 0xffff0000, v172
	v_lshlrev_b32_e32 v57, 16, v173
	v_and_b32_e32 v61, 0xffff0000, v173
	v_add_f32_e32 v46, v46, v54
	v_add_f32_e32 v50, v50, v58
	v_add_f32_e32 v47, v47, v55
	v_add_f32_e32 v51, v51, v59
	v_add_f32_e32 v48, v48, v56
	v_add_f32_e32 v52, v52, v60
	v_add_f32_e32 v49, v49, v57
	v_add_f32_e32 v53, v53, v61
	v_lshlrev_b32_e32 v54, 16, v190
	v_and_b32_e32 v58, 0xffff0000, v190
	v_lshlrev_b32_e32 v55, 16, v191
	v_and_b32_e32 v59, 0xffff0000, v191
	v_lshlrev_b32_e32 v56, 16, v192
	v_and_b32_e32 v60, 0xffff0000, v192
	v_lshlrev_b32_e32 v57, 16, v193
	v_and_b32_e32 v61, 0xffff0000, v193
	v_add_f32_e32 v46, v46, v54
	v_add_f32_e32 v50, v50, v58
	v_add_f32_e32 v47, v47, v55
	v_add_f32_e32 v51, v51, v59
	v_add_f32_e32 v48, v48, v56
	v_add_f32_e32 v52, v52, v60
	v_add_f32_e32 v49, v49, v57
	v_add_f32_e32 v53, v53, v61
	v_fma_f32 v46, v42, v46, -v54
	v_fma_f32 v50, v42, v50, -v58
	v_fma_f32 v47, v42, v47, -v55
	v_fma_f32 v51, v42, v51, -v59
	v_fma_f32 v48, v42, v48, -v56
	v_fma_f32 v52, v42, v52, -v60
	v_fma_f32 v49, v42, v49, -v57
	v_fma_f32 v53, v42, v53, -v61
	v_cvt_pk_bf16_f32 v46, v46, v50
	v_cvt_pk_bf16_f32 v47, v47, v51
	v_cvt_pk_bf16_f32 v48, v48, v52
	v_cvt_pk_bf16_f32 v49, v49, v53
	global_store_dwordx4 v44, v[46:49], s[62:63] offset:1024
	v_add_u32_e32 v44, 0x800000, v44
	global_load_dwordx4 v[190:193], v43, s[80:81]
	v_subrev_u32_e32 v45, s30, v43
	global_load_dwordx4 v[194:197], v45, s[80:81]
	s_mov_b64 exec, s[12:13]
	v_subrev_u32_e32 v45, s30, v45
	global_load_dwordx4 v[198:201], v45, s[80:81]
	v_subrev_u32_e32 v45, s30, v45
	global_load_dwordx4 v[202:205], v45, s[80:81]
	s_mov_b64 exec, s[14:15]
	v_subrev_u32_e32 v45, s30, v45
	global_load_dwordx4 v[206:209], v45, s[80:81]
	v_subrev_u32_e32 v45, s30, v45
	global_load_dwordx4 v[210:213], v45, s[80:81]
	v_subrev_u32_e32 v45, s30, v45
	global_load_dwordx4 v[214:217], v45, s[80:81]
	v_subrev_u32_e32 v45, s30, v45
	global_load_dwordx4 v[218:221], v45, s[80:81]
	s_mov_b64 exec, s[16:17]
	v_subrev_u32_e32 v45, s30, v45
	global_load_dwordx4 v[222:225], v45, s[80:81]
	v_subrev_u32_e32 v45, s30, v45
	global_load_dwordx4 v[226:229], v45, s[80:81]
	v_subrev_u32_e32 v45, s30, v45
	global_load_dwordx4 v[230:233], v45, s[80:81]
	v_subrev_u32_e32 v45, s30, v45
	global_load_dwordx4 v[234:237], v45, s[80:81]
	v_subrev_u32_e32 v45, s30, v45
	global_load_dwordx4 v[238:241], v45, s[80:81]
	v_subrev_u32_e32 v45, s30, v45
	global_load_dwordx4 v[242:245], v45, s[80:81]
	v_subrev_u32_e32 v45, s30, v45
	global_load_dwordx4 v[246:249], v45, s[80:81]
	v_subrev_u32_e32 v45, s30, v45
	global_load_dwordx4 v[170:173], v45, s[80:81]
	s_mov_b64 exec, -1
	v_add_u32_e32 v43, s11, v43
	s_waitcnt vmcnt(17)
	v_lshlrev_b32_e32 v54, 16, v100
	v_and_b32_e32 v58, 0xffff0000, v100
	v_lshlrev_b32_e32 v55, 16, v101
	v_and_b32_e32 v59, 0xffff0000, v101
	v_lshlrev_b32_e32 v56, 16, v102
	v_and_b32_e32 v60, 0xffff0000, v102
	v_lshlrev_b32_e32 v57, 16, v103
	v_and_b32_e32 v61, 0xffff0000, v103
	v_add_f32_e32 v46, 0, v54
	v_add_f32_e32 v50, 0, v58
	v_add_f32_e32 v47, 0, v55
	v_add_f32_e32 v51, 0, v59
	v_add_f32_e32 v48, 0, v56
	v_add_f32_e32 v52, 0, v60
	v_add_f32_e32 v49, 0, v57
	v_add_f32_e32 v53, 0, v61
	v_lshlrev_b32_e32 v54, 16, v104
	v_and_b32_e32 v58, 0xffff0000, v104
	v_lshlrev_b32_e32 v55, 16, v105
	v_and_b32_e32 v59, 0xffff0000, v105
	v_lshlrev_b32_e32 v56, 16, v106
	v_and_b32_e32 v60, 0xffff0000, v106
	v_lshlrev_b32_e32 v57, 16, v107
	v_and_b32_e32 v61, 0xffff0000, v107
	v_add_f32_e32 v46, v46, v54
	v_add_f32_e32 v50, v50, v58
	v_add_f32_e32 v47, v47, v55
	v_add_f32_e32 v51, v51, v59
	v_add_f32_e32 v48, v48, v56
	v_add_f32_e32 v52, v52, v60
	v_add_f32_e32 v49, v49, v57
	v_add_f32_e32 v53, v53, v61
	v_lshlrev_b32_e32 v54, 16, v108
	v_and_b32_e32 v58, 0xffff0000, v108
	v_lshlrev_b32_e32 v55, 16, v109
	v_and_b32_e32 v59, 0xffff0000, v109
	v_lshlrev_b32_e32 v56, 16, v110
	v_and_b32_e32 v60, 0xffff0000, v110
	v_lshlrev_b32_e32 v57, 16, v111
	v_and_b32_e32 v61, 0xffff0000, v111
	v_add_f32_e32 v46, v46, v54
	v_add_f32_e32 v50, v50, v58
	v_add_f32_e32 v47, v47, v55
	v_add_f32_e32 v51, v51, v59
	v_add_f32_e32 v48, v48, v56
	v_add_f32_e32 v52, v52, v60
	v_add_f32_e32 v49, v49, v57
	v_add_f32_e32 v53, v53, v61
	v_lshlrev_b32_e32 v54, 16, v112
	v_and_b32_e32 v58, 0xffff0000, v112
	v_lshlrev_b32_e32 v55, 16, v113
	v_and_b32_e32 v59, 0xffff0000, v113
	v_lshlrev_b32_e32 v56, 16, v114
	v_and_b32_e32 v60, 0xffff0000, v114
	v_lshlrev_b32_e32 v57, 16, v115
	v_and_b32_e32 v61, 0xffff0000, v115
	v_add_f32_e32 v46, v46, v54
	v_add_f32_e32 v50, v50, v58
	v_add_f32_e32 v47, v47, v55
	v_add_f32_e32 v51, v51, v59
	v_add_f32_e32 v48, v48, v56
	v_add_f32_e32 v52, v52, v60
	v_add_f32_e32 v49, v49, v57
	v_add_f32_e32 v53, v53, v61
	v_lshlrev_b32_e32 v54, 16, v116
	v_and_b32_e32 v58, 0xffff0000, v116
	v_lshlrev_b32_e32 v55, 16, v117
	v_and_b32_e32 v59, 0xffff0000, v117
	v_lshlrev_b32_e32 v56, 16, v118
	v_and_b32_e32 v60, 0xffff0000, v118
	v_lshlrev_b32_e32 v57, 16, v119
	v_and_b32_e32 v61, 0xffff0000, v119
	v_add_f32_e32 v46, v46, v54
	v_add_f32_e32 v50, v50, v58
	v_add_f32_e32 v47, v47, v55
	v_add_f32_e32 v51, v51, v59
	v_add_f32_e32 v48, v48, v56
	v_add_f32_e32 v52, v52, v60
	v_add_f32_e32 v49, v49, v57
	v_add_f32_e32 v53, v53, v61
	v_lshlrev_b32_e32 v54, 16, v120
	v_and_b32_e32 v58, 0xffff0000, v120
	v_lshlrev_b32_e32 v55, 16, v121
	v_and_b32_e32 v59, 0xffff0000, v121
	v_lshlrev_b32_e32 v56, 16, v122
	v_and_b32_e32 v60, 0xffff0000, v122
	v_lshlrev_b32_e32 v57, 16, v123
	v_and_b32_e32 v61, 0xffff0000, v123
	v_add_f32_e32 v46, v46, v54
	v_add_f32_e32 v50, v50, v58
	v_add_f32_e32 v47, v47, v55
	v_add_f32_e32 v51, v51, v59
	v_add_f32_e32 v48, v48, v56
	v_add_f32_e32 v52, v52, v60
	v_add_f32_e32 v49, v49, v57
	v_add_f32_e32 v53, v53, v61
	v_lshlrev_b32_e32 v54, 16, v124
	v_and_b32_e32 v58, 0xffff0000, v124
	v_lshlrev_b32_e32 v55, 16, v125
	v_and_b32_e32 v59, 0xffff0000, v125
	v_lshlrev_b32_e32 v56, 16, v126
	v_and_b32_e32 v60, 0xffff0000, v126
	v_lshlrev_b32_e32 v57, 16, v127
	v_and_b32_e32 v61, 0xffff0000, v127
	v_add_f32_e32 v46, v46, v54
	v_add_f32_e32 v50, v50, v58
	v_add_f32_e32 v47, v47, v55
	v_add_f32_e32 v51, v51, v59
	v_add_f32_e32 v48, v48, v56
	v_add_f32_e32 v52, v52, v60
	v_add_f32_e32 v49, v49, v57
	v_add_f32_e32 v53, v53, v61
	v_lshlrev_b32_e32 v54, 16, v128
	v_and_b32_e32 v58, 0xffff0000, v128
	v_lshlrev_b32_e32 v55, 16, v129
	v_and_b32_e32 v59, 0xffff0000, v129
	v_lshlrev_b32_e32 v56, 16, v130
	v_and_b32_e32 v60, 0xffff0000, v130
	v_lshlrev_b32_e32 v57, 16, v131
	v_and_b32_e32 v61, 0xffff0000, v131
	v_add_f32_e32 v46, v46, v54
	v_add_f32_e32 v50, v50, v58
	v_add_f32_e32 v47, v47, v55
	v_add_f32_e32 v51, v51, v59
	v_add_f32_e32 v48, v48, v56
	v_add_f32_e32 v52, v52, v60
	v_add_f32_e32 v49, v49, v57
	v_add_f32_e32 v53, v53, v61
	v_lshlrev_b32_e32 v54, 16, v132
	v_and_b32_e32 v58, 0xffff0000, v132
	v_lshlrev_b32_e32 v55, 16, v133
	v_and_b32_e32 v59, 0xffff0000, v133
	v_lshlrev_b32_e32 v56, 16, v134
	v_and_b32_e32 v60, 0xffff0000, v134
	v_lshlrev_b32_e32 v57, 16, v135
	v_and_b32_e32 v61, 0xffff0000, v135
	v_add_f32_e32 v46, v46, v54
	v_add_f32_e32 v50, v50, v58
	v_add_f32_e32 v47, v47, v55
	v_add_f32_e32 v51, v51, v59
	v_add_f32_e32 v48, v48, v56
	v_add_f32_e32 v52, v52, v60
	v_add_f32_e32 v49, v49, v57
	v_add_f32_e32 v53, v53, v61
	v_lshlrev_b32_e32 v54, 16, v136
	v_and_b32_e32 v58, 0xffff0000, v136
	v_lshlrev_b32_e32 v55, 16, v137
	v_and_b32_e32 v59, 0xffff0000, v137
	v_lshlrev_b32_e32 v56, 16, v138
	v_and_b32_e32 v60, 0xffff0000, v138
	v_lshlrev_b32_e32 v57, 16, v139
	v_and_b32_e32 v61, 0xffff0000, v139
	v_add_f32_e32 v46, v46, v54
	v_add_f32_e32 v50, v50, v58
	v_add_f32_e32 v47, v47, v55
	v_add_f32_e32 v51, v51, v59
	v_add_f32_e32 v48, v48, v56
	v_add_f32_e32 v52, v52, v60
	v_add_f32_e32 v49, v49, v57
	v_add_f32_e32 v53, v53, v61
	v_lshlrev_b32_e32 v54, 16, v140
	v_and_b32_e32 v58, 0xffff0000, v140
	v_lshlrev_b32_e32 v55, 16, v141
	v_and_b32_e32 v59, 0xffff0000, v141
	v_lshlrev_b32_e32 v56, 16, v142
	v_and_b32_e32 v60, 0xffff0000, v142
	v_lshlrev_b32_e32 v57, 16, v143
	v_and_b32_e32 v61, 0xffff0000, v143
	v_add_f32_e32 v46, v46, v54
	v_add_f32_e32 v50, v50, v58
	v_add_f32_e32 v47, v47, v55
	v_add_f32_e32 v51, v51, v59
	v_add_f32_e32 v48, v48, v56
	v_add_f32_e32 v52, v52, v60
	v_add_f32_e32 v49, v49, v57
	v_add_f32_e32 v53, v53, v61
	v_lshlrev_b32_e32 v54, 16, v144
	v_and_b32_e32 v58, 0xffff0000, v144
	v_lshlrev_b32_e32 v55, 16, v145
	v_and_b32_e32 v59, 0xffff0000, v145
	v_lshlrev_b32_e32 v56, 16, v146
	v_and_b32_e32 v60, 0xffff0000, v146
	v_lshlrev_b32_e32 v57, 16, v147
	v_and_b32_e32 v61, 0xffff0000, v147
	v_add_f32_e32 v46, v46, v54
	v_add_f32_e32 v50, v50, v58
	v_add_f32_e32 v47, v47, v55
	v_add_f32_e32 v51, v51, v59
	v_add_f32_e32 v48, v48, v56
	v_add_f32_e32 v52, v52, v60
	v_add_f32_e32 v49, v49, v57
	v_add_f32_e32 v53, v53, v61
	v_lshlrev_b32_e32 v54, 16, v158
	v_and_b32_e32 v58, 0xffff0000, v158
	v_lshlrev_b32_e32 v55, 16, v159
	v_and_b32_e32 v59, 0xffff0000, v159
	v_lshlrev_b32_e32 v56, 16, v160
	v_and_b32_e32 v60, 0xffff0000, v160
	v_lshlrev_b32_e32 v57, 16, v161
	v_and_b32_e32 v61, 0xffff0000, v161
	v_add_f32_e32 v46, v46, v54
	v_add_f32_e32 v50, v50, v58
	v_add_f32_e32 v47, v47, v55
	v_add_f32_e32 v51, v51, v59
	v_add_f32_e32 v48, v48, v56
	v_add_f32_e32 v52, v52, v60
	v_add_f32_e32 v49, v49, v57
	v_add_f32_e32 v53, v53, v61
	v_lshlrev_b32_e32 v54, 16, v162
	v_and_b32_e32 v58, 0xffff0000, v162
	v_lshlrev_b32_e32 v55, 16, v163
	v_and_b32_e32 v59, 0xffff0000, v163
	v_lshlrev_b32_e32 v56, 16, v164
	v_and_b32_e32 v60, 0xffff0000, v164
	v_lshlrev_b32_e32 v57, 16, v165
	v_and_b32_e32 v61, 0xffff0000, v165
	v_add_f32_e32 v46, v46, v54
	v_add_f32_e32 v50, v50, v58
	v_add_f32_e32 v47, v47, v55
	v_add_f32_e32 v51, v51, v59
	v_add_f32_e32 v48, v48, v56
	v_add_f32_e32 v52, v52, v60
	v_add_f32_e32 v49, v49, v57
	v_add_f32_e32 v53, v53, v61
	v_lshlrev_b32_e32 v54, 16, v166
	v_and_b32_e32 v58, 0xffff0000, v166
	v_lshlrev_b32_e32 v55, 16, v167
	v_and_b32_e32 v59, 0xffff0000, v167
	v_lshlrev_b32_e32 v56, 16, v168
	v_and_b32_e32 v60, 0xffff0000, v168
	v_lshlrev_b32_e32 v57, 16, v169
	v_and_b32_e32 v61, 0xffff0000, v169
	v_add_f32_e32 v46, v46, v54
	v_add_f32_e32 v50, v50, v58
	v_add_f32_e32 v47, v47, v55
	v_add_f32_e32 v51, v51, v59
	v_add_f32_e32 v48, v48, v56
	v_add_f32_e32 v52, v52, v60
	v_add_f32_e32 v49, v49, v57
	v_add_f32_e32 v53, v53, v61
	v_lshlrev_b32_e32 v54, 16, v96
	v_and_b32_e32 v58, 0xffff0000, v96
	v_lshlrev_b32_e32 v55, 16, v97
	v_and_b32_e32 v59, 0xffff0000, v97
	v_lshlrev_b32_e32 v56, 16, v98
	v_and_b32_e32 v60, 0xffff0000, v98
	v_lshlrev_b32_e32 v57, 16, v99
	v_and_b32_e32 v61, 0xffff0000, v99
	v_add_f32_e32 v46, v46, v54
	v_add_f32_e32 v50, v50, v58
	v_add_f32_e32 v47, v47, v55
	v_add_f32_e32 v51, v51, v59
	v_add_f32_e32 v48, v48, v56
	v_add_f32_e32 v52, v52, v60
	v_add_f32_e32 v49, v49, v57
	v_add_f32_e32 v53, v53, v61
	v_fma_f32 v46, v42, v46, -v54
	v_fma_f32 v50, v42, v50, -v58
	v_fma_f32 v47, v42, v47, -v55
	v_fma_f32 v51, v42, v51, -v59
	v_fma_f32 v48, v42, v48, -v56
	v_fma_f32 v52, v42, v52, -v60
	v_fma_f32 v49, v42, v49, -v57
	v_fma_f32 v53, v42, v53, -v61
	v_cvt_pk_bf16_f32 v46, v46, v50
	v_cvt_pk_bf16_f32 v47, v47, v51
	v_cvt_pk_bf16_f32 v48, v48, v52
	v_cvt_pk_bf16_f32 v49, v49, v53
	global_store_dwordx4 v44, v[46:49], s[62:63] offset:1024
	v_add_u32_e32 v44, 0x800000, v44
	s_waitcnt vmcnt(1)
	v_lshlrev_b32_e32 v54, 16, v194
	v_and_b32_e32 v58, 0xffff0000, v194
	v_lshlrev_b32_e32 v55, 16, v195
	v_and_b32_e32 v59, 0xffff0000, v195
	v_lshlrev_b32_e32 v56, 16, v196
	v_and_b32_e32 v60, 0xffff0000, v196
	v_lshlrev_b32_e32 v57, 16, v197
	v_and_b32_e32 v61, 0xffff0000, v197
	v_add_f32_e32 v46, 0, v54
	v_add_f32_e32 v50, 0, v58
	v_add_f32_e32 v47, 0, v55
	v_add_f32_e32 v51, 0, v59
	v_add_f32_e32 v48, 0, v56
	v_add_f32_e32 v52, 0, v60
	v_add_f32_e32 v49, 0, v57
	v_add_f32_e32 v53, 0, v61
	v_lshlrev_b32_e32 v54, 16, v198
	v_and_b32_e32 v58, 0xffff0000, v198
	v_lshlrev_b32_e32 v55, 16, v199
	v_and_b32_e32 v59, 0xffff0000, v199
	v_lshlrev_b32_e32 v56, 16, v200
	v_and_b32_e32 v60, 0xffff0000, v200
	v_lshlrev_b32_e32 v57, 16, v201
	v_and_b32_e32 v61, 0xffff0000, v201
	v_add_f32_e32 v46, v46, v54
	v_add_f32_e32 v50, v50, v58
	v_add_f32_e32 v47, v47, v55
	v_add_f32_e32 v51, v51, v59
	v_add_f32_e32 v48, v48, v56
	v_add_f32_e32 v52, v52, v60
	v_add_f32_e32 v49, v49, v57
	v_add_f32_e32 v53, v53, v61
	v_lshlrev_b32_e32 v54, 16, v202
	v_and_b32_e32 v58, 0xffff0000, v202
	v_lshlrev_b32_e32 v55, 16, v203
	v_and_b32_e32 v59, 0xffff0000, v203
	v_lshlrev_b32_e32 v56, 16, v204
	v_and_b32_e32 v60, 0xffff0000, v204
	v_lshlrev_b32_e32 v57, 16, v205
	v_and_b32_e32 v61, 0xffff0000, v205
	v_add_f32_e32 v46, v46, v54
	v_add_f32_e32 v50, v50, v58
	v_add_f32_e32 v47, v47, v55
	v_add_f32_e32 v51, v51, v59
	v_add_f32_e32 v48, v48, v56
	v_add_f32_e32 v52, v52, v60
	v_add_f32_e32 v49, v49, v57
	v_add_f32_e32 v53, v53, v61
	v_lshlrev_b32_e32 v54, 16, v206
	v_and_b32_e32 v58, 0xffff0000, v206
	v_lshlrev_b32_e32 v55, 16, v207
	v_and_b32_e32 v59, 0xffff0000, v207
	v_lshlrev_b32_e32 v56, 16, v208
	v_and_b32_e32 v60, 0xffff0000, v208
	v_lshlrev_b32_e32 v57, 16, v209
	v_and_b32_e32 v61, 0xffff0000, v209
	v_add_f32_e32 v46, v46, v54
	v_add_f32_e32 v50, v50, v58
	v_add_f32_e32 v47, v47, v55
	v_add_f32_e32 v51, v51, v59
	v_add_f32_e32 v48, v48, v56
	v_add_f32_e32 v52, v52, v60
	v_add_f32_e32 v49, v49, v57
	v_add_f32_e32 v53, v53, v61
	v_lshlrev_b32_e32 v54, 16, v210
	v_and_b32_e32 v58, 0xffff0000, v210
	v_lshlrev_b32_e32 v55, 16, v211
	v_and_b32_e32 v59, 0xffff0000, v211
	v_lshlrev_b32_e32 v56, 16, v212
	v_and_b32_e32 v60, 0xffff0000, v212
	v_lshlrev_b32_e32 v57, 16, v213
	v_and_b32_e32 v61, 0xffff0000, v213
	v_add_f32_e32 v46, v46, v54
	v_add_f32_e32 v50, v50, v58
	v_add_f32_e32 v47, v47, v55
	v_add_f32_e32 v51, v51, v59
	v_add_f32_e32 v48, v48, v56
	v_add_f32_e32 v52, v52, v60
	v_add_f32_e32 v49, v49, v57
	v_add_f32_e32 v53, v53, v61
	v_lshlrev_b32_e32 v54, 16, v214
	v_and_b32_e32 v58, 0xffff0000, v214
	v_lshlrev_b32_e32 v55, 16, v215
	v_and_b32_e32 v59, 0xffff0000, v215
	v_lshlrev_b32_e32 v56, 16, v216
	v_and_b32_e32 v60, 0xffff0000, v216
	v_lshlrev_b32_e32 v57, 16, v217
	v_and_b32_e32 v61, 0xffff0000, v217
	v_add_f32_e32 v46, v46, v54
	v_add_f32_e32 v50, v50, v58
	v_add_f32_e32 v47, v47, v55
	v_add_f32_e32 v51, v51, v59
	v_add_f32_e32 v48, v48, v56
	v_add_f32_e32 v52, v52, v60
	v_add_f32_e32 v49, v49, v57
	v_add_f32_e32 v53, v53, v61
	v_lshlrev_b32_e32 v54, 16, v218
	v_and_b32_e32 v58, 0xffff0000, v218
	v_lshlrev_b32_e32 v55, 16, v219
	v_and_b32_e32 v59, 0xffff0000, v219
	v_lshlrev_b32_e32 v56, 16, v220
	v_and_b32_e32 v60, 0xffff0000, v220
	v_lshlrev_b32_e32 v57, 16, v221
	v_and_b32_e32 v61, 0xffff0000, v221
	v_add_f32_e32 v46, v46, v54
	v_add_f32_e32 v50, v50, v58
	v_add_f32_e32 v47, v47, v55
	v_add_f32_e32 v51, v51, v59
	v_add_f32_e32 v48, v48, v56
	v_add_f32_e32 v52, v52, v60
	v_add_f32_e32 v49, v49, v57
	v_add_f32_e32 v53, v53, v61
	v_lshlrev_b32_e32 v54, 16, v222
	v_and_b32_e32 v58, 0xffff0000, v222
	v_lshlrev_b32_e32 v55, 16, v223
	v_and_b32_e32 v59, 0xffff0000, v223
	v_lshlrev_b32_e32 v56, 16, v224
	v_and_b32_e32 v60, 0xffff0000, v224
	v_lshlrev_b32_e32 v57, 16, v225
	v_and_b32_e32 v61, 0xffff0000, v225
	v_add_f32_e32 v46, v46, v54
	v_add_f32_e32 v50, v50, v58
	v_add_f32_e32 v47, v47, v55
	v_add_f32_e32 v51, v51, v59
	v_add_f32_e32 v48, v48, v56
	v_add_f32_e32 v52, v52, v60
	v_add_f32_e32 v49, v49, v57
	v_add_f32_e32 v53, v53, v61
	v_lshlrev_b32_e32 v54, 16, v226
	v_and_b32_e32 v58, 0xffff0000, v226
	v_lshlrev_b32_e32 v55, 16, v227
	v_and_b32_e32 v59, 0xffff0000, v227
	v_lshlrev_b32_e32 v56, 16, v228
	v_and_b32_e32 v60, 0xffff0000, v228
	v_lshlrev_b32_e32 v57, 16, v229
	v_and_b32_e32 v61, 0xffff0000, v229
	v_add_f32_e32 v46, v46, v54
	v_add_f32_e32 v50, v50, v58
	v_add_f32_e32 v47, v47, v55
	v_add_f32_e32 v51, v51, v59
	v_add_f32_e32 v48, v48, v56
	v_add_f32_e32 v52, v52, v60
	v_add_f32_e32 v49, v49, v57
	v_add_f32_e32 v53, v53, v61
	v_lshlrev_b32_e32 v54, 16, v230
	v_and_b32_e32 v58, 0xffff0000, v230
	v_lshlrev_b32_e32 v55, 16, v231
	v_and_b32_e32 v59, 0xffff0000, v231
	v_lshlrev_b32_e32 v56, 16, v232
	v_and_b32_e32 v60, 0xffff0000, v232
	v_lshlrev_b32_e32 v57, 16, v233
	v_and_b32_e32 v61, 0xffff0000, v233
	v_add_f32_e32 v46, v46, v54
	v_add_f32_e32 v50, v50, v58
	v_add_f32_e32 v47, v47, v55
	v_add_f32_e32 v51, v51, v59
	v_add_f32_e32 v48, v48, v56
	v_add_f32_e32 v52, v52, v60
	v_add_f32_e32 v49, v49, v57
	v_add_f32_e32 v53, v53, v61
	v_lshlrev_b32_e32 v54, 16, v234
	v_and_b32_e32 v58, 0xffff0000, v234
	v_lshlrev_b32_e32 v55, 16, v235
	v_and_b32_e32 v59, 0xffff0000, v235
	v_lshlrev_b32_e32 v56, 16, v236
	v_and_b32_e32 v60, 0xffff0000, v236
	v_lshlrev_b32_e32 v57, 16, v237
	v_and_b32_e32 v61, 0xffff0000, v237
	v_add_f32_e32 v46, v46, v54
	v_add_f32_e32 v50, v50, v58
	v_add_f32_e32 v47, v47, v55
	v_add_f32_e32 v51, v51, v59
	v_add_f32_e32 v48, v48, v56
	v_add_f32_e32 v52, v52, v60
	v_add_f32_e32 v49, v49, v57
	v_add_f32_e32 v53, v53, v61
	v_lshlrev_b32_e32 v54, 16, v238
	v_and_b32_e32 v58, 0xffff0000, v238
	v_lshlrev_b32_e32 v55, 16, v239
	v_and_b32_e32 v59, 0xffff0000, v239
	v_lshlrev_b32_e32 v56, 16, v240
	v_and_b32_e32 v60, 0xffff0000, v240
	v_lshlrev_b32_e32 v57, 16, v241
	v_and_b32_e32 v61, 0xffff0000, v241
	v_add_f32_e32 v46, v46, v54
	v_add_f32_e32 v50, v50, v58
	v_add_f32_e32 v47, v47, v55
	v_add_f32_e32 v51, v51, v59
	v_add_f32_e32 v48, v48, v56
	v_add_f32_e32 v52, v52, v60
	v_add_f32_e32 v49, v49, v57
	v_add_f32_e32 v53, v53, v61
	v_lshlrev_b32_e32 v54, 16, v242
	v_and_b32_e32 v58, 0xffff0000, v242
	v_lshlrev_b32_e32 v55, 16, v243
	v_and_b32_e32 v59, 0xffff0000, v243
	v_lshlrev_b32_e32 v56, 16, v244
	v_and_b32_e32 v60, 0xffff0000, v244
	v_lshlrev_b32_e32 v57, 16, v245
	v_and_b32_e32 v61, 0xffff0000, v245
	v_add_f32_e32 v46, v46, v54
	v_add_f32_e32 v50, v50, v58
	v_add_f32_e32 v47, v47, v55
	v_add_f32_e32 v51, v51, v59
	v_add_f32_e32 v48, v48, v56
	v_add_f32_e32 v52, v52, v60
	v_add_f32_e32 v49, v49, v57
	v_add_f32_e32 v53, v53, v61
	v_lshlrev_b32_e32 v54, 16, v246
	v_and_b32_e32 v58, 0xffff0000, v246
	v_lshlrev_b32_e32 v55, 16, v247
	v_and_b32_e32 v59, 0xffff0000, v247
	v_lshlrev_b32_e32 v56, 16, v248
	v_and_b32_e32 v60, 0xffff0000, v248
	v_lshlrev_b32_e32 v57, 16, v249
	v_and_b32_e32 v61, 0xffff0000, v249
	v_add_f32_e32 v46, v46, v54
	v_add_f32_e32 v50, v50, v58
	v_add_f32_e32 v47, v47, v55
	v_add_f32_e32 v51, v51, v59
	v_add_f32_e32 v48, v48, v56
	v_add_f32_e32 v52, v52, v60
	v_add_f32_e32 v49, v49, v57
	v_add_f32_e32 v53, v53, v61
	v_lshlrev_b32_e32 v54, 16, v170
	v_and_b32_e32 v58, 0xffff0000, v170
	v_lshlrev_b32_e32 v55, 16, v171
	v_and_b32_e32 v59, 0xffff0000, v171
	v_lshlrev_b32_e32 v56, 16, v172
	v_and_b32_e32 v60, 0xffff0000, v172
	v_lshlrev_b32_e32 v57, 16, v173
	v_and_b32_e32 v61, 0xffff0000, v173
	v_add_f32_e32 v46, v46, v54
	v_add_f32_e32 v50, v50, v58
	v_add_f32_e32 v47, v47, v55
	v_add_f32_e32 v51, v51, v59
	v_add_f32_e32 v48, v48, v56
	v_add_f32_e32 v52, v52, v60
	v_add_f32_e32 v49, v49, v57
	v_add_f32_e32 v53, v53, v61
	v_lshlrev_b32_e32 v54, 16, v190
	v_and_b32_e32 v58, 0xffff0000, v190
	v_lshlrev_b32_e32 v55, 16, v191
	v_and_b32_e32 v59, 0xffff0000, v191
	v_lshlrev_b32_e32 v56, 16, v192
	v_and_b32_e32 v60, 0xffff0000, v192
	v_lshlrev_b32_e32 v57, 16, v193
	v_and_b32_e32 v61, 0xffff0000, v193
	v_add_f32_e32 v46, v46, v54
	v_add_f32_e32 v50, v50, v58
	v_add_f32_e32 v47, v47, v55
	v_add_f32_e32 v51, v51, v59
	v_add_f32_e32 v48, v48, v56
	v_add_f32_e32 v52, v52, v60
	v_add_f32_e32 v49, v49, v57
	v_add_f32_e32 v53, v53, v61
	v_fma_f32 v46, v42, v46, -v54
	v_fma_f32 v50, v42, v50, -v58
	v_fma_f32 v47, v42, v47, -v55
	v_fma_f32 v51, v42, v51, -v59
	v_fma_f32 v48, v42, v48, -v56
	v_fma_f32 v52, v42, v52, -v60
	v_fma_f32 v49, v42, v49, -v57
	v_fma_f32 v53, v42, v53, -v61
	v_cvt_pk_bf16_f32 v46, v46, v50
	v_cvt_pk_bf16_f32 v47, v47, v51
	v_cvt_pk_bf16_f32 v48, v48, v52
	v_cvt_pk_bf16_f32 v49, v49, v53
	global_store_dwordx4 v44, v[46:49], s[62:63] offset:1024
	v_add_u32_e32 v44, 0x800000, v44
	s_branch .LBB0_254
.Lpool_slow:
	v_readlane_b32 s2, v254, 44
	v_mov_b32_e32 v72, v0
	s_nop 0
	v_lshl_add_u32 v3, v1, 3, s2
	s_mov_b64 s[2:3], 0
	s_branch .LBB0_224
